# chain step: ot convert+store block moved under the first state-update MFMA group, LDS staging of next tiles moved mid-step with recounted vmcnt, static s_setprio 1 for waves 4-7 inside the chain
# baseline (speedup 1.0000x reference)
; #define CH_LOAD_V(SET, st) do { const int gc_ = CH_GC(CH_CLAMP(st)); _Pragma("unroll") for (int ks = 0; ks < 4; ++ks) vf##SET[ks] = *(const bf16x8*)(vtg + ((size_t)(gc_ * 4 + h) * 256 + 32 * wave + l32) * 64 + 16 * ks + 8 * hh); } while (0)
; #define CH_STAGE(SET, buf) do { *(LAS u32x4*)((buf) + qt0 * 272 + qc0 * 16) = q0##SET; *(LAS u32x4*)((buf) + (qt0 + 32) * 272 + qc0 * 16) = q1##SET; \
;         *(LAS u32x4*)((buf) + CH_OFFK + kd0 * 144 + kc0 * 16) = k0##SET; *(LAS u32x4*)((buf) + CH_OFFK + (kd0 + 64) * 144 + kc0 * 16) = k1##SET; \
;         if (tid < 32) *(LAS f32x4*)((buf) + CH_OFFE + tid * 16) = en##SET; } while (0)
; __device__ __forceinline__ void gla_chain(LAS unsigned char* lds, int ci, int nchunk, bf16_t* proj, const bf16_t* kltf, const bf16_t* kltb, const bf16_t* vtg, const float* ef, const float* eb, bf16_t* ob, bf16_t* of2, unsigned* done, bf16_t* dry = nullptr) {
;     int tid = threadIdx.x; asm volatile("" : "+v"(tid));
;     const int lane = tid & 63, wave = __builtin_amdgcn_readfirstlane(tid >> 6);
;     const int dir = ci & 1, bh = ci >> 1, b = bh >> 2, h = bh & 3, l32 = lane & 31, hh = lane >> 5;
;     const bf16_t* klt = dir ? kltb : kltf; const float* ee = dir ? eb : ef;
;     const int qcol = (dir ? C_KA : C_QA) + h * 128;
;     const int qt0 = tid >> 4, qc0 = tid & 15;
;     const int kd0 = tid >> 3, kc0 = tid & 7;
;     f32x16 S[4];
; #pragma unroll
;     for (int i = 0; i < 4; ++i) S[i] = f32x16{};
;     ...
;     u32x4 q0A, q1A, k0A, k1A, q0B, q1B, k0B, k1B; f32x4 enA = (f32x4){0.f, 0.f, 0.f, 0.f}, enB = enA; bf16x8 vfA[4], vfB[4];
;     CH_LOAD_T(A, 0); CH_LOAD_V(A, 0);
;     CH_STAGE(A, lds);
;     CH_LOAD_T(B, 1); CH_LOAD_V(B, 1);
.LBB0_193:
	s_or_b64 exec, exec, s[8:9]
	s_cmp_lt_u32 s38, 0x100
	s_cbranch_scc1 .Lchain_prio_skip
	s_setprio 1
.Lchain_prio_skip:
	s_ashr_i32 s8, s38, 1
	s_andn2_b32 s8, s8, 31
	s_lshl_b64 s[2:3], s[2:3], 8
	s_ashr_i32 s9, s8, 31
	s_add_u32 s2, s2, s8
	v_and_b32_e32 v219, 31, v217
	s_addc_u32 s3, s3, s9
	v_or_b32_e32 v28, s2, v219
	v_mov_b32_e32 v29, s3
	v_readlane_b32 s2, v254, 40
	v_bfe_u32 v25, v217, 5, 1
	v_lshlrev_b64 v[28:29], 7, v[28:29]
	v_readlane_b32 s3, v254, 41
	v_lshlrev_b32_e32 v186, 4, v25
	v_mov_b32_e32 v187, v1
	v_lshl_add_u64 v[28:29], s[2:3], 0, v[28:29]
	v_lshl_add_u64 v[28:29], v[28:29], 0, v[186:187]
	global_load_dwordx4 v[114:117], v[28:29], off
	global_load_dwordx4 v[110:113], v[28:29], off offset:32
	global_load_dwordx4 v[106:109], v[28:29], off offset:64
	global_load_dwordx4 v[102:105], v[28:29], off offset:96
	s_movk_i32 s2, 0x110
	v_mul_lo_u32 v28, v218, s2
	v_add_u32_e32 v28, 0, v28
	v_add_u32_e32 v187, v28, v0
	v_mul_lo_u32 v0, v20, s30
	v_add_u32_e32 v0, 0, v0
	v_add_u32_e32 v220, v0, v24
	s_waitcnt vmcnt(7)
	ds_write_b128 v187, v[2:5]
	s_waitcnt vmcnt(6)
	ds_write_b128 v187, v[6:9] offset:8704
	s_waitcnt vmcnt(5)
	ds_write_b128 v220, v[10:13] offset:17408
	s_waitcnt vmcnt(4)
	ds_write_b128 v220, v[14:17] offset:26624
	s_and_saveexec_b64 s[2:3], vcc
	v_lshl_add_u32 v0, v217, 4, 0
	ds_write_b128 v0, v[98:101] offset:35840
	s_or_b64 exec, exec, s[2:3]
	s_and_b64 s[2:3], s[4:5], exec
	v_readlane_b32 s2, v254, 63
	s_cselect_b32 s2, 1, s2
	s_add_i32 s14, s2, s37
	v_lshl_add_u32 v9, s14, 6, v218
	v_mov_b64_e32 v[4:5], s[94:95]
	v_lshlrev_b32_e32 v0, 3, v27
	v_mad_i64_i32 v[2:3], s[2:3], v9, s28, v[4:5]
	v_lshl_add_u64 v[6:7], v[2:3], 0, s[66:67]
	v_lshlrev_b32_e32 v2, 1, v0
	v_add_u32_e32 v0, 32, v9
	v_mad_i64_i32 v[4:5], s[2:3], v0, s28, v[4:5]
	s_lshl_b32 s2, s14, 2
	s_or_b32 s2, s2, s12
	s_ashr_i32 s3, s2, 31
	s_lshl_b64 s[14:15], s[2:3], 14
	v_mov_b32_e32 v3, v1
	v_lshl_add_u64 v[4:5], v[4:5], 0, s[66:67]
	s_add_u32 s14, s36, s14
	v_lshlrev_b64 v[188:189], 6, v[20:21]
	v_lshlrev_b32_e32 v8, 3, v26
	v_lshl_add_u64 v[6:7], v[6:7], 0, v[2:3]
	v_lshl_add_u64 v[4:5], v[4:5], 0, v[2:3]
	s_addc_u32 s15, s13, s15
	v_lshlrev_b64 v[198:199], 6, v[22:23]
	global_load_dwordx4 v[118:121], v[6:7], off
	global_load_dwordx4 v[122:125], v[4:5], off
	v_lshl_add_u64 v[4:5], v[188:189], 1, s[14:15]
	v_lshlrev_b32_e32 v0, 1, v8
	v_lshl_add_u64 v[4:5], v[4:5], 0, v[0:1]
	v_lshl_add_u64 v[6:7], v[198:199], 1, s[14:15]
	v_lshl_add_u64 v[6:7], v[6:7], 0, v[0:1]
	global_load_dwordx4 v[130:133], v[4:5], off
	global_load_dwordx4 v[134:137], v[6:7], off
	s_and_saveexec_b64 s[14:15], s[0:1]
	s_xor_b64 s[0:1], exec, s[14:15]
	v_mov_b32_e32 v19, v1
	s_or_saveexec_b64 s[0:1], s[0:1]
	v_mov_b32_e32 v126, v1
	v_mov_b32_e32 v127, v1
	v_mov_b32_e32 v128, v1
	v_mov_b32_e32 v129, v1
	s_xor_b64 exec, exec, s[0:1]
	s_cbranch_execz .LBB0_199
	s_lshl_b64 s[14:15], s[2:3], 9
	s_add_u32 s14, s6, s14
	s_addc_u32 s15, s7, s15
	v_lshl_add_u64 v[4:5], v[18:19], 2, s[14:15]
	global_load_dwordx4 v[126:129], v[4:5], off

; __device__ __forceinline__ void gla_chain(LAS unsigned char* lds, int ci, int nchunk, bf16_t* proj, const bf16_t* kltf, const bf16_t* kltb, const bf16_t* vtg, const float* ef, const float* eb, bf16_t* ob, bf16_t* of2, unsigned* done, bf16_t* dry = nullptr) {
;     ...
;     for (int step = 0; step < nchunk; step += 2) {
;         CH_STEP(step, A, B);
;         CH_STEP(step + 1, B, A);
;     }
.LBB0_200:
	s_waitcnt lgkmcnt(0)
	s_add_i32 s8, s8, 2
	s_add_i32 s6, s6, -2
	s_add_i32 s2, s2, 1
	s_cmp_ge_u32 s2, s81
	s_barrier
	s_cbranch_scc1 .LBB0_209

.LBB0_203:
	s_or_b64 exec, exec, s[2:3]
	v_add_u32_e32 v190, 0x2000, v224
	ds_read2_b64 v[66:69], v224 offset1:2
	ds_read2_b64 v[170:173], v224 offset0:4 offset1:6
	ds_read2_b64 v[70:73], v190 offset0:64 offset1:66
	ds_read2_b64 v[174:177], v190 offset0:68 offset1:70
	ds_read2_b64 v[178:181], v224 offset0:8 offset1:10
	ds_read2_b64 v[182:185], v190 offset0:72 offset1:74
	ds_read2_b64 v[234:237], v224 offset0:12 offset1:14
	ds_read2_b64 v[238:241], v190 offset0:76 offset1:78
	s_add_i32 s7, s8, -3
	s_and_b64 s[2:3], s[4:5], exec
	s_cselect_b32 s2, s7, s6
	s_add_i32 s2, s2, s37
	v_cvt_pk_bf16_f32 v74, v50, v51
	v_cvt_pk_bf16_f32 v75, v52, v53
	v_cvt_pk_bf16_f32 v76, v54, v55
	v_cvt_pk_bf16_f32 v77, v56, v57
	v_cvt_pk_bf16_f32 v242, v58, v59
	v_cvt_pk_bf16_f32 v243, v60, v61
	s_waitcnt lgkmcnt(7)
	v_mfma_f32_32x32x16_bf16 v[82:97], v[74:77], v[66:69], 0
	v_cvt_pk_bf16_f32 v244, v62, v63
	v_cvt_pk_bf16_f32 v245, v64, v65
	s_waitcnt lgkmcnt(5)
	v_mfma_f32_32x32x16_bf16 v[66:81], v[74:77], v[70:73], 0
	v_mfma_f32_32x32x16_bf16 v[82:97], v[242:245], v[170:173], v[82:97]
	s_waitcnt lgkmcnt(4)
	v_mfma_f32_32x32x16_bf16 v[66:81], v[242:245], v[174:177], v[66:81]
	ds_read2_b64 v[170:173], v224 offset0:16 offset1:18
	ds_read2_b64 v[174:177], v224 offset0:20 offset1:22
	ds_read2_b64 v[242:245], v190 offset0:80 offset1:82
	ds_read2_b64 v[246:249], v190 offset0:84 offset1:86
	v_cvt_pk_bf16_f32 v194, v34, v35
	v_cvt_pk_bf16_f32 v195, v36, v37
	v_cvt_pk_bf16_f32 v196, v38, v39
	v_cvt_pk_bf16_f32 v197, v40, v41
	s_waitcnt lgkmcnt(7)
	s_nop 0
	v_mfma_f32_32x32x16_bf16 v[82:97], v[194:197], v[178:181], v[82:97]
	v_cvt_pk_bf16_f32 v178, v42, v43
	v_cvt_pk_bf16_f32 v179, v44, v45
	v_cvt_pk_bf16_f32 v180, v46, v47
	v_cvt_pk_bf16_f32 v181, v48, v49
	s_waitcnt lgkmcnt(6)
	v_mfma_f32_32x32x16_bf16 v[66:81], v[194:197], v[182:185], v[66:81]
	s_waitcnt lgkmcnt(5)
	v_mfma_f32_32x32x16_bf16 v[82:97], v[178:181], v[234:237], v[82:97]
	s_waitcnt lgkmcnt(4)
	v_mfma_f32_32x32x16_bf16 v[66:81], v[178:181], v[238:241], v[66:81]
	ds_read2_b64 v[194:197], v224 offset0:24 offset1:26
	ds_read2_b64 v[234:237], v224 offset0:28 offset1:30
	ds_read2_b64 v[238:241], v190 offset0:88 offset1:90
	ds_read2_b64 v[190:193], v190 offset0:92 offset1:94
	v_cvt_pk_bf16_f32 v178, v18, v19
	v_cvt_pk_bf16_f32 v179, v20, v21
	v_cvt_pk_bf16_f32 v180, v22, v23
	v_cvt_pk_bf16_f32 v181, v24, v25
	s_waitcnt lgkmcnt(7)
	s_nop 0
	v_mfma_f32_32x32x16_bf16 v[82:97], v[178:181], v[170:173], v[82:97]
	v_cvt_pk_bf16_f32 v170, v26, v27
	v_cvt_pk_bf16_f32 v171, v28, v29
	v_cvt_pk_bf16_f32 v172, v30, v31
	v_cvt_pk_bf16_f32 v173, v32, v33
	s_waitcnt lgkmcnt(5)
	v_mfma_f32_32x32x16_bf16 v[66:81], v[178:181], v[242:245], v[66:81]
	v_mfma_f32_32x32x16_bf16 v[82:97], v[170:173], v[174:177], v[82:97]
	s_waitcnt lgkmcnt(4)
	v_mfma_f32_32x32x16_bf16 v[66:81], v[170:173], v[246:249], v[66:81]
	ds_read_b128 v[182:185], v226 offset:17408
	ds_read_b128 v[178:181], v226 offset:17440
	ds_read_b128 v[174:177], v226 offset:17472
	ds_read_b128 v[170:173], v226 offset:17504
	v_cvt_pk_bf16_f32 v242, v2, v3
	v_cvt_pk_bf16_f32 v243, v4, v5
	v_cvt_pk_bf16_f32 v244, v6, v7
	v_cvt_pk_bf16_f32 v245, v8, v9
	s_waitcnt lgkmcnt(7)
	s_nop 0
	v_mfma_f32_32x32x16_bf16 v[82:97], v[242:245], v[194:197], v[82:97]
	v_cvt_pk_bf16_f32 v194, v10, v11
	v_cvt_pk_bf16_f32 v195, v12, v13
	v_cvt_pk_bf16_f32 v196, v14, v15
	v_cvt_pk_bf16_f32 v197, v16, v17
	s_waitcnt lgkmcnt(5)
	v_mfma_f32_32x32x16_bf16 v[66:81], v[242:245], v[238:241], v[66:81]
	v_mfma_f32_32x32x16_bf16 v[82:97], v[194:197], v[234:237], v[82:97]
	s_waitcnt lgkmcnt(4)
	v_mfma_f32_32x32x16_bf16 v[66:81], v[194:197], v[190:193], v[66:81]
	ds_read_b128 v[190:193], v221 offset:35840
	ds_read_b128 v[194:197], v221 offset:35872
	ds_read_b128 v[234:237], v221 offset:35904
	ds_read_b128 v[238:241], v221 offset:35936
	s_waitcnt lgkmcnt(3)
	v_mul_f32_e32 v52, v52, v192
	v_mul_f32_e32 v53, v53, v193
	s_waitcnt lgkmcnt(2)
	v_mul_f32_e32 v56, v56, v196
	v_mul_f32_e32 v57, v57, v197
	s_waitcnt lgkmcnt(1)
	v_mul_f32_e32 v60, v60, v236
	v_mul_f32_e32 v61, v61, v237
	s_waitcnt lgkmcnt(0)
	v_mul_f32_e32 v64, v64, v240
	v_mul_f32_e32 v65, v65, v241
	v_mul_f32_e32 v62, v62, v238
	v_mul_f32_e32 v63, v63, v239
	v_mul_f32_e32 v58, v58, v234
	v_mul_f32_e32 v59, v59, v235
	v_mul_f32_e32 v54, v54, v194
	v_mul_f32_e32 v55, v55, v195
	v_mul_f32_e32 v50, v50, v190
	v_mul_f32_e32 v51, v51, v191
	ds_read_b128 v[190:193], v221 offset:35968
	ds_read_b128 v[194:197], v221 offset:36000
	ds_read_b128 v[234:237], v221 offset:36032
	ds_read_b128 v[238:241], v221 offset:36064
	s_waitcnt lgkmcnt(3)
	v_mul_f32_e32 v36, v36, v192
	v_mul_f32_e32 v37, v37, v193
	s_waitcnt lgkmcnt(2)
	v_mul_f32_e32 v40, v40, v196
	v_mul_f32_e32 v41, v41, v197
	s_waitcnt lgkmcnt(1)
	v_mul_f32_e32 v44, v44, v236
	v_mul_f32_e32 v45, v45, v237
	s_waitcnt lgkmcnt(0)
	v_mul_f32_e32 v48, v48, v240
	v_mul_f32_e32 v49, v49, v241
	v_mul_f32_e32 v46, v46, v238
	v_mul_f32_e32 v47, v47, v239
	v_mul_f32_e32 v42, v42, v234
	v_mul_f32_e32 v43, v43, v235
	v_mul_f32_e32 v38, v38, v194
	v_mul_f32_e32 v39, v39, v195
	v_mul_f32_e32 v34, v34, v190
	v_mul_f32_e32 v35, v35, v191
	ds_read_b128 v[190:193], v221 offset:36096
	ds_read_b128 v[194:197], v221 offset:36128
	ds_read_b128 v[234:237], v221 offset:36160
	ds_read_b128 v[238:241], v221 offset:36192
	s_waitcnt lgkmcnt(3)
	v_mul_f32_e32 v20, v20, v192
	v_mul_f32_e32 v21, v21, v193
	s_waitcnt lgkmcnt(2)
	v_mul_f32_e32 v24, v24, v196
	v_mul_f32_e32 v25, v25, v197
	s_waitcnt lgkmcnt(1)
	v_mul_f32_e32 v28, v28, v236
	v_mul_f32_e32 v29, v29, v237
	s_waitcnt lgkmcnt(0)
	v_mul_f32_e32 v32, v32, v240
	v_mul_f32_e32 v33, v33, v241
	v_mul_f32_e32 v30, v30, v238
	v_mul_f32_e32 v31, v31, v239
	v_mul_f32_e32 v26, v26, v234
	v_mul_f32_e32 v27, v27, v235
	v_mul_f32_e32 v22, v22, v194
	v_mul_f32_e32 v23, v23, v195
	v_mul_f32_e32 v18, v18, v190
	v_mul_f32_e32 v19, v19, v191
	ds_read_b128 v[190:193], v221 offset:36224
	ds_read_b128 v[194:197], v221 offset:36256
	ds_read_b128 v[234:237], v221 offset:36288
	ds_read_b128 v[238:241], v221 offset:36320
	s_waitcnt lgkmcnt(3)
	v_mul_f32_e32 v4, v4, v192
	v_mul_f32_e32 v5, v5, v193
	s_waitcnt lgkmcnt(2)
	v_mul_f32_e32 v8, v8, v196
	v_mul_f32_e32 v9, v9, v197
	s_waitcnt lgkmcnt(1)
	v_mul_f32_e32 v12, v12, v236
	v_mul_f32_e32 v13, v13, v237
	s_waitcnt lgkmcnt(0)
	v_mul_f32_e32 v16, v16, v240
	v_mul_f32_e32 v17, v17, v241
	v_mul_f32_e32 v14, v14, v238
	v_mul_f32_e32 v15, v15, v239
	v_mul_f32_e32 v10, v10, v234
	v_mul_f32_e32 v11, v11, v235
	v_mul_f32_e32 v6, v6, v194
	v_mul_f32_e32 v7, v7, v195
	v_mul_f32_e32 v2, v2, v190
	v_mul_f32_e32 v3, v3, v191
	ds_read_b128 v[190:193], v227 offset:17408
	ds_read_b128 v[194:197], v227 offset:17440
	ds_read_b128 v[234:237], v227 offset:17472
	ds_read_b128 v[238:241], v227 offset:17504
	s_waitcnt vmcnt(15)
	v_mfma_f32_32x32x16_bf16 v[50:65], v[182:185], v[114:117], v[50:65]
	s_waitcnt vmcnt(14)
	v_mfma_f32_32x32x16_bf16 v[50:65], v[178:181], v[110:113], v[50:65]
	s_waitcnt vmcnt(13)
	v_mfma_f32_32x32x16_bf16 v[50:65], v[174:177], v[106:109], v[50:65]
	s_waitcnt vmcnt(12)
	v_mfma_f32_32x32x16_bf16 v[50:65], v[170:173], v[102:105], v[50:65]
	v_lshl_or_b32 v242, s2, 6, v219
	v_ashrrev_i32_e32 v243, 31, v242
	v_lshlrev_b64 v[244:245], 11, v[242:243]
	v_lshl_add_u64 v[244:245], v[202:203], 0, v[244:245]
	v_cvt_pk_bf16_f32 v82, v82, v83
	v_cvt_pk_bf16_f32 v83, v84, v85
	v_cvt_pk_bf16_f32 v84, v90, v91
	v_cvt_pk_bf16_f32 v85, v92, v93
	v_cvt_pk_bf16_f32 v86, v86, v87
	v_cvt_pk_bf16_f32 v87, v88, v89
	v_cvt_pk_bf16_f32 v88, v94, v95
	v_cvt_pk_bf16_f32 v89, v96, v97
	v_or_b32_e32 v90, 32, v242
	v_ashrrev_i32_e32 v91, 31, v90
	v_permlane32_swap_b32_e32 v82, v84
	v_permlane32_swap_b32_e32 v83, v85
	v_permlane32_swap_b32_e32 v86, v88
	v_permlane32_swap_b32_e32 v87, v89
	global_store_dwordx4 v[244:245], v[82:85], off
	global_store_dwordx4 v[244:245], v[86:89], off offset:16
	v_lshlrev_b64 v[90:91], 11, v[90:91]
	v_lshl_add_u64 v[90:91], v[202:203], 0, v[90:91]
	v_cvt_pk_bf16_f32 v66, v66, v67
	v_cvt_pk_bf16_f32 v67, v68, v69
	v_cvt_pk_bf16_f32 v68, v74, v75
	v_cvt_pk_bf16_f32 v69, v76, v77
	v_cvt_pk_bf16_f32 v70, v70, v71
	v_cvt_pk_bf16_f32 v71, v72, v73
	v_cvt_pk_bf16_f32 v72, v78, v79
	v_cvt_pk_bf16_f32 v73, v80, v81
	s_nop 1
	v_permlane32_swap_b32_e32 v66, v68
	v_permlane32_swap_b32_e32 v67, v69
	v_permlane32_swap_b32_e32 v70, v72
	v_permlane32_swap_b32_e32 v71, v73
	global_store_dwordx4 v[90:91], v[66:69], off
	global_store_dwordx4 v[90:91], v[70:73], off offset:16
	s_waitcnt vmcnt(15)
	ds_write_b128 v187, v[118:121] offset:36864
	s_waitcnt vmcnt(14)
	ds_write_b128 v187, v[122:125] offset:45568
	s_waitcnt vmcnt(13)
	ds_write_b128 v220, v[130:133] offset:54272
	s_waitcnt vmcnt(12)
	ds_write_b128 v220, v[134:137] offset:63488
	s_and_saveexec_b64 s[14:15], vcc
	v_add_u32_e32 v66, 0x11c00, v228
	ds_write_b128 v66, v[126:129]
	s_or_b64 exec, exec, s[14:15]
	ds_read_b128 v[170:173], v225 offset:26624
	ds_read_b128 v[174:177], v225 offset:26656
	ds_read_b128 v[178:181], v225 offset:26688
	ds_read_b128 v[182:185], v225 offset:26720
	s_waitcnt lgkmcnt(7)
	v_mfma_f32_32x32x16_bf16 v[34:49], v[190:193], v[114:117], v[34:49]
	s_waitcnt lgkmcnt(6)
	v_mfma_f32_32x32x16_bf16 v[34:49], v[194:197], v[110:113], v[34:49]
	s_waitcnt lgkmcnt(5)
	v_mfma_f32_32x32x16_bf16 v[34:49], v[234:237], v[106:109], v[34:49]
	s_waitcnt lgkmcnt(4)
	v_mfma_f32_32x32x16_bf16 v[34:49], v[238:241], v[102:105], v[34:49]
	ds_read_b128 v[190:193], v225 offset:31232
	ds_read_b128 v[194:197], v225 offset:31264
	ds_read_b128 v[234:237], v225 offset:31296
	ds_read_b128 v[238:241], v225 offset:31328
	s_waitcnt lgkmcnt(7)
	v_mfma_f32_32x32x16_bf16 v[18:33], v[170:173], v[114:117], v[18:33]
	s_waitcnt lgkmcnt(6)
	v_mfma_f32_32x32x16_bf16 v[18:33], v[174:177], v[110:113], v[18:33]
	s_waitcnt lgkmcnt(5)
	v_mfma_f32_32x32x16_bf16 v[18:33], v[178:181], v[106:109], v[18:33]
	s_waitcnt lgkmcnt(4)
	v_mfma_f32_32x32x16_bf16 v[18:33], v[182:185], v[102:105], v[18:33]
	s_waitcnt lgkmcnt(3)
	v_mfma_f32_32x32x16_bf16 v[2:17], v[190:193], v[114:117], v[2:17]
	s_waitcnt lgkmcnt(2)
	v_mfma_f32_32x32x16_bf16 v[2:17], v[194:197], v[110:113], v[2:17]
	s_waitcnt lgkmcnt(1)
	v_mfma_f32_32x32x16_bf16 v[2:17], v[234:237], v[106:109], v[2:17]
	s_waitcnt lgkmcnt(0)
	v_mfma_f32_32x32x16_bf16 v[2:17], v[238:241], v[102:105], v[2:17]
	s_lshl_b64 s[0:1], s[0:1], 15
	v_lshl_add_u64 v[102:103], v[206:207], 0, s[0:1]
	global_load_dwordx4 v[114:117], v[102:103], off
	global_load_dwordx4 v[110:113], v[102:103], off offset:32
	global_load_dwordx4 v[106:109], v[102:103], off offset:64
	s_nop 0
	global_load_dwordx4 v[102:105], v[102:103], off offset:96
	v_mov_b32_e32 v66, s8
	s_min_u32 s2, s8, s52
	v_sub_u32_e64 v66, s52, v66 clamp
	s_and_b64 s[0:1], s[4:5], exec
	v_readfirstlane_b32 s0, v66
	s_cselect_b32 s0, s2, s0
	s_add_i32 s2, s0, s37
	v_lshl_add_u32 v68, s2, 6, v218
	v_mad_i64_i32 v[66:67], s[0:1], v68, s28, v[200:201]
	v_add_u32_e32 v68, 32, v68
	v_mad_i64_i32 v[68:69], s[0:1], v68, s28, v[200:201]
	s_lshl_b32 s0, s2, 2
	s_or_b32 s0, s0, s12
	s_ashr_i32 s1, s0, 31
	s_lshl_b64 s[2:3], s[0:1], 14
	s_add_u32 s2, s36, s2
	s_addc_u32 s3, s13, s3
	s_waitcnt lgkmcnt(0)
	s_barrier
	global_load_dwordx4 v[118:121], v[66:67], off
	global_load_dwordx4 v[122:125], v[68:69], off
	v_lshl_add_u64 v[66:67], v[188:189], 1, s[2:3]
	v_lshl_add_u64 v[66:67], v[66:67], 0, v[0:1]
	v_lshl_add_u64 v[68:69], v[198:199], 1, s[2:3]
	v_lshl_add_u64 v[68:69], v[68:69], 0, v[0:1]
	global_load_dwordx4 v[130:133], v[66:67], off
	global_load_dwordx4 v[134:137], v[68:69], off
	s_and_saveexec_b64 s[2:3], vcc
	s_cbranch_execz .LBB0_207
	s_lshl_b64 s[14:15], s[0:1], 9
	v_lshl_add_u64 v[66:67], v[204:205], 0, s[14:15]
	global_load_dwordx4 v[126:129], v[66:67], off
.LBB0_207:
	s_or_b64 exec, exec, s[2:3]
	v_add_u32_e32 v229, 0x9000, v224
	v_add_u32_e32 v246, 0xb000, v224
	ds_read2_b64 v[66:69], v229 offset1:2
	ds_read2_b64 v[170:173], v229 offset0:4 offset1:6
	ds_read2_b64 v[70:73], v246 offset0:64 offset1:66
	ds_read2_b64 v[174:177], v246 offset0:68 offset1:70
	ds_read2_b64 v[178:181], v229 offset0:8 offset1:10
	ds_read2_b64 v[182:185], v246 offset0:72 offset1:74
	ds_read2_b64 v[190:193], v229 offset0:12 offset1:14
	ds_read2_b64 v[194:197], v246 offset0:76 offset1:78
	s_xor_b32 s2, s7, 0x3fffffe
	s_add_i32 s3, s2, s81
	s_add_i32 s2, s7, 1
	s_and_b64 s[14:15], s[4:5], exec
	s_cselect_b32 s3, s2, s3
	s_add_i32 s3, s3, s37
	v_cvt_pk_bf16_f32 v74, v50, v51
	v_cvt_pk_bf16_f32 v75, v52, v53
	v_cvt_pk_bf16_f32 v76, v54, v55
	v_cvt_pk_bf16_f32 v77, v56, v57
	v_cvt_pk_bf16_f32 v234, v58, v59
	v_cvt_pk_bf16_f32 v235, v60, v61
	s_waitcnt lgkmcnt(7)
	v_mfma_f32_32x32x16_bf16 v[82:97], v[74:77], v[66:69], 0
	v_cvt_pk_bf16_f32 v236, v62, v63
	v_cvt_pk_bf16_f32 v237, v64, v65
	s_waitcnt lgkmcnt(5)
	v_mfma_f32_32x32x16_bf16 v[66:81], v[74:77], v[70:73], 0
	v_mfma_f32_32x32x16_bf16 v[82:97], v[234:237], v[170:173], v[82:97]
	s_waitcnt lgkmcnt(4)
	v_mfma_f32_32x32x16_bf16 v[66:81], v[234:237], v[174:177], v[66:81]
	ds_read2_b64 v[170:173], v229 offset0:16 offset1:18
	ds_read2_b64 v[174:177], v229 offset0:20 offset1:22
	ds_read2_b64 v[234:237], v246 offset0:80 offset1:82
	ds_read2_b64 v[238:241], v246 offset0:84 offset1:86
	v_cvt_pk_bf16_f32 v242, v34, v35
	v_cvt_pk_bf16_f32 v243, v36, v37
	v_cvt_pk_bf16_f32 v244, v38, v39
	v_cvt_pk_bf16_f32 v245, v40, v41
	s_waitcnt lgkmcnt(7)
	s_nop 0
	v_mfma_f32_32x32x16_bf16 v[82:97], v[242:245], v[178:181], v[82:97]
	v_cvt_pk_bf16_f32 v178, v42, v43
	v_cvt_pk_bf16_f32 v179, v44, v45
	v_cvt_pk_bf16_f32 v180, v46, v47
	v_cvt_pk_bf16_f32 v181, v48, v49
	s_waitcnt lgkmcnt(6)
	v_mfma_f32_32x32x16_bf16 v[66:81], v[242:245], v[182:185], v[66:81]
	s_waitcnt lgkmcnt(5)
	v_mfma_f32_32x32x16_bf16 v[82:97], v[178:181], v[190:193], v[82:97]
	s_waitcnt lgkmcnt(4)
	v_mfma_f32_32x32x16_bf16 v[66:81], v[178:181], v[194:197], v[66:81]
	ds_read2_b64 v[190:193], v229 offset0:24 offset1:26
	ds_read2_b64 v[194:197], v229 offset0:28 offset1:30
	ds_read2_b64 v[242:245], v246 offset0:88 offset1:90
	ds_read2_b64 v[246:249], v246 offset0:92 offset1:94
	v_cvt_pk_bf16_f32 v178, v18, v19
	v_cvt_pk_bf16_f32 v179, v20, v21
	v_cvt_pk_bf16_f32 v180, v22, v23
	v_cvt_pk_bf16_f32 v181, v24, v25
	s_waitcnt lgkmcnt(7)
	s_nop 0
	v_mfma_f32_32x32x16_bf16 v[82:97], v[178:181], v[170:173], v[82:97]
	v_cvt_pk_bf16_f32 v170, v26, v27
	v_cvt_pk_bf16_f32 v171, v28, v29
	v_cvt_pk_bf16_f32 v172, v30, v31
	v_cvt_pk_bf16_f32 v173, v32, v33
	s_waitcnt lgkmcnt(5)
	v_mfma_f32_32x32x16_bf16 v[66:81], v[178:181], v[234:237], v[66:81]
	v_mfma_f32_32x32x16_bf16 v[82:97], v[170:173], v[174:177], v[82:97]
	s_waitcnt lgkmcnt(4)
	v_mfma_f32_32x32x16_bf16 v[66:81], v[170:173], v[238:241], v[66:81]
	ds_read_b128 v[182:185], v226 offset:54272
	ds_read_b128 v[178:181], v226 offset:54304
	ds_read_b128 v[174:177], v226 offset:54336
	ds_read_b128 v[170:173], v226 offset:54368
	v_cvt_pk_bf16_f32 v234, v2, v3
	v_cvt_pk_bf16_f32 v235, v4, v5
	v_cvt_pk_bf16_f32 v236, v6, v7
	v_cvt_pk_bf16_f32 v237, v8, v9
	s_waitcnt lgkmcnt(7)
	s_nop 0
	v_mfma_f32_32x32x16_bf16 v[82:97], v[234:237], v[190:193], v[82:97]
	v_cvt_pk_bf16_f32 v190, v10, v11
	v_cvt_pk_bf16_f32 v191, v12, v13
	v_cvt_pk_bf16_f32 v192, v14, v15
	v_cvt_pk_bf16_f32 v193, v16, v17
	s_waitcnt lgkmcnt(5)
	v_mfma_f32_32x32x16_bf16 v[66:81], v[234:237], v[242:245], v[66:81]
	v_mfma_f32_32x32x16_bf16 v[82:97], v[190:193], v[194:197], v[82:97]
	s_waitcnt lgkmcnt(4)
	v_mfma_f32_32x32x16_bf16 v[66:81], v[190:193], v[246:249], v[66:81]
	v_add_u32_e32 v190, 0, v186
	v_add_u32_e32 v229, 0x11c00, v190
	ds_read_b128 v[190:193], v229
	ds_read_b128 v[194:197], v229 offset:32
	ds_read_b128 v[234:237], v229 offset:64
	ds_read_b128 v[238:241], v229 offset:96
	s_waitcnt lgkmcnt(3)
	v_mul_f32_e32 v52, v52, v192
	v_mul_f32_e32 v53, v53, v193
	s_waitcnt lgkmcnt(2)
	v_mul_f32_e32 v54, v54, v194
	v_mul_f32_e32 v55, v55, v195
	s_waitcnt lgkmcnt(1)
	v_mul_f32_e32 v58, v58, v234
	v_mul_f32_e32 v59, v59, v235
	s_waitcnt lgkmcnt(0)
	v_mul_f32_e32 v62, v62, v238
	v_mul_f32_e32 v63, v63, v239
	v_mul_f32_e32 v64, v64, v240
	v_mul_f32_e32 v65, v65, v241
	v_mul_f32_e32 v60, v60, v236
	v_mul_f32_e32 v61, v61, v237
	v_mul_f32_e32 v56, v56, v196
	v_mul_f32_e32 v57, v57, v197
	v_mul_f32_e32 v50, v50, v190
	v_mul_f32_e32 v51, v51, v191
	ds_read_b128 v[190:193], v229 offset:128
	ds_read_b128 v[194:197], v229 offset:160
	ds_read_b128 v[234:237], v229 offset:192
	ds_read_b128 v[238:241], v229 offset:224
	s_waitcnt lgkmcnt(3)
	v_mul_f32_e32 v36, v36, v192
	v_mul_f32_e32 v37, v37, v193
	s_waitcnt lgkmcnt(2)
	v_mul_f32_e32 v38, v38, v194
	v_mul_f32_e32 v39, v39, v195
	s_waitcnt lgkmcnt(1)
	v_mul_f32_e32 v42, v42, v234
	v_mul_f32_e32 v43, v43, v235
	s_waitcnt lgkmcnt(0)
	v_mul_f32_e32 v46, v46, v238
	v_mul_f32_e32 v47, v47, v239
	v_mul_f32_e32 v48, v48, v240
	v_mul_f32_e32 v49, v49, v241
	v_mul_f32_e32 v44, v44, v236
	v_mul_f32_e32 v45, v45, v237
	v_mul_f32_e32 v40, v40, v196
	v_mul_f32_e32 v41, v41, v197
	v_mul_f32_e32 v34, v34, v190
	v_mul_f32_e32 v35, v35, v191
	ds_read_b128 v[190:193], v229 offset:256
	ds_read_b128 v[194:197], v229 offset:288
	ds_read_b128 v[234:237], v229 offset:320
	ds_read_b128 v[238:241], v229 offset:352
	s_waitcnt lgkmcnt(3)
	v_mul_f32_e32 v20, v20, v192
	v_mul_f32_e32 v21, v21, v193
	s_waitcnt lgkmcnt(2)
	v_mul_f32_e32 v22, v22, v194
	v_mul_f32_e32 v23, v23, v195
	s_waitcnt lgkmcnt(1)
; __device__ __forceinline__ unsigned xb_add(unsigned* p, unsigned v) { return __hip_atomic_fetch_add(p, v, __ATOMIC_RELAXED, __HIP_MEMORY_SCOPE_AGENT); }
; __device__ __forceinline__ void gla_chain(LAS unsigned char* lds, int ci, int nchunk, bf16_t* proj, const bf16_t* kltf, const bf16_t* kltb, const bf16_t* vtg, const float* ef, const float* eb, bf16_t* ob, bf16_t* of2, unsigned* done, bf16_t* dry = nullptr) {
;     ...
;     for (int step = 0; step < nchunk; step += 2) {
;         CH_STEP(step, A, B);
;         CH_STEP(step + 1, B, A);
;     }
;     if (done) {
;         asm volatile("s_waitcnt vmcnt(0)" ::: "memory");
;         __syncthreads();
;         if (tid == 0) { __builtin_amdgcn_fence(__ATOMIC_RELEASE, "agent"); asm volatile("s_waitcnt vmcnt(0)" ::: "memory"); (void)xb_add(done + 64 * b, 1u); }
	v_mul_f32_e32 v26, v26, v234
	v_mul_f32_e32 v27, v27, v235
	s_waitcnt lgkmcnt(0)
	v_mul_f32_e32 v30, v30, v238
	v_mul_f32_e32 v31, v31, v239
	v_mul_f32_e32 v32, v32, v240
	v_mul_f32_e32 v33, v33, v241
	v_mul_f32_e32 v28, v28, v236
	v_mul_f32_e32 v29, v29, v237
	v_mul_f32_e32 v24, v24, v196
	v_mul_f32_e32 v25, v25, v197
	v_mul_f32_e32 v18, v18, v190
	v_mul_f32_e32 v19, v19, v191
	ds_read_b128 v[190:193], v229 offset:384
	ds_read_b128 v[194:197], v229 offset:416
	ds_read_b128 v[234:237], v229 offset:448
	ds_read_b128 v[238:241], v229 offset:480
	s_waitcnt lgkmcnt(3)
	v_mul_f32_e32 v4, v4, v192
	v_mul_f32_e32 v5, v5, v193
	s_waitcnt lgkmcnt(2)
	v_mul_f32_e32 v6, v6, v194
	v_mul_f32_e32 v7, v7, v195
	s_waitcnt lgkmcnt(1)
	v_mul_f32_e32 v10, v10, v234
	v_mul_f32_e32 v11, v11, v235
	s_waitcnt lgkmcnt(0)
	v_mul_f32_e32 v14, v14, v238
	v_mul_f32_e32 v15, v15, v239
	v_mul_f32_e32 v16, v16, v240
	v_mul_f32_e32 v17, v17, v241
	v_mul_f32_e32 v12, v12, v236
	v_mul_f32_e32 v13, v13, v237
	v_mul_f32_e32 v8, v8, v196
	v_mul_f32_e32 v9, v9, v197
	v_mul_f32_e32 v2, v2, v190
	v_mul_f32_e32 v3, v3, v191
	ds_read_b128 v[190:193], v227 offset:54272
	ds_read_b128 v[194:197], v227 offset:54304
	ds_read_b128 v[234:237], v227 offset:54336
	ds_read_b128 v[238:241], v227 offset:54368
	s_waitcnt vmcnt(19)
	v_mfma_f32_32x32x16_bf16 v[50:65], v[182:185], v[150:153], v[50:65]
	s_waitcnt vmcnt(18)
	v_mfma_f32_32x32x16_bf16 v[50:65], v[178:181], v[146:149], v[50:65]
	s_waitcnt vmcnt(17)
	v_mfma_f32_32x32x16_bf16 v[50:65], v[174:177], v[142:145], v[50:65]
	s_waitcnt vmcnt(16)
	v_mfma_f32_32x32x16_bf16 v[50:65], v[170:173], v[138:141], v[50:65]
	v_lshl_or_b32 v242, s3, 6, v219
	v_ashrrev_i32_e32 v243, 31, v242
	v_lshlrev_b64 v[244:245], 11, v[242:243]
	v_lshl_add_u64 v[244:245], v[202:203], 0, v[244:245]
	v_cvt_pk_bf16_f32 v82, v82, v83
	v_cvt_pk_bf16_f32 v83, v84, v85
	v_cvt_pk_bf16_f32 v84, v90, v91
	v_cvt_pk_bf16_f32 v85, v92, v93
	v_cvt_pk_bf16_f32 v86, v86, v87
	v_cvt_pk_bf16_f32 v87, v88, v89
	v_cvt_pk_bf16_f32 v88, v94, v95
	v_cvt_pk_bf16_f32 v89, v96, v97
	v_or_b32_e32 v90, 32, v242
	v_ashrrev_i32_e32 v91, 31, v90
	v_permlane32_swap_b32_e32 v82, v84
	v_permlane32_swap_b32_e32 v83, v85
	v_permlane32_swap_b32_e32 v86, v88
	v_permlane32_swap_b32_e32 v87, v89
	global_store_dwordx4 v[244:245], v[82:85], off
	global_store_dwordx4 v[244:245], v[86:89], off offset:16
	v_lshlrev_b64 v[90:91], 11, v[90:91]
	v_lshl_add_u64 v[90:91], v[202:203], 0, v[90:91]
	v_cvt_pk_bf16_f32 v66, v66, v67
	v_cvt_pk_bf16_f32 v67, v68, v69
	v_cvt_pk_bf16_f32 v68, v74, v75
	v_cvt_pk_bf16_f32 v69, v76, v77
	v_cvt_pk_bf16_f32 v70, v70, v71
	v_cvt_pk_bf16_f32 v71, v72, v73
	v_cvt_pk_bf16_f32 v72, v78, v79
	v_cvt_pk_bf16_f32 v73, v80, v81
	s_nop 1
	v_permlane32_swap_b32_e32 v66, v68
	v_permlane32_swap_b32_e32 v67, v69
	v_permlane32_swap_b32_e32 v70, v72
	v_permlane32_swap_b32_e32 v71, v73
	global_store_dwordx4 v[90:91], v[66:69], off
	global_store_dwordx4 v[90:91], v[70:73], off offset:16
	s_waitcnt vmcnt(19)
	ds_write_b128 v187, v[154:157]
	s_waitcnt vmcnt(18)
	ds_write_b128 v187, v[158:161] offset:8704
	s_waitcnt vmcnt(17)
	ds_write_b128 v220, v[162:165] offset:17408
	s_waitcnt vmcnt(16)
	ds_write_b128 v220, v[166:169] offset:26624
	s_and_saveexec_b64 s[14:15], vcc
	ds_write_b128 v228, v[98:101] offset:35840
	s_or_b64 exec, exec, s[14:15]
	ds_read_b128 v[170:173], v222 offset:63488
	ds_read_b128 v[174:177], v222 offset:63520
	ds_read_b128 v[178:181], v222 offset:63552
	ds_read_b128 v[182:185], v222 offset:63584
	s_waitcnt lgkmcnt(7)
	v_mfma_f32_32x32x16_bf16 v[34:49], v[190:193], v[150:153], v[34:49]
	s_waitcnt lgkmcnt(6)
	v_mfma_f32_32x32x16_bf16 v[34:49], v[194:197], v[146:149], v[34:49]
	s_waitcnt lgkmcnt(5)
	v_mfma_f32_32x32x16_bf16 v[34:49], v[234:237], v[142:145], v[34:49]
	s_waitcnt lgkmcnt(4)
	v_mfma_f32_32x32x16_bf16 v[34:49], v[238:241], v[138:141], v[34:49]
	ds_read_b128 v[190:193], v223 offset:13824
	ds_read_b128 v[194:197], v223 offset:13856
	ds_read_b128 v[234:237], v223 offset:13888
	ds_read_b128 v[238:241], v223 offset:13920
	s_waitcnt lgkmcnt(7)
	v_mfma_f32_32x32x16_bf16 v[18:33], v[170:173], v[150:153], v[18:33]
	s_waitcnt lgkmcnt(6)
	v_mfma_f32_32x32x16_bf16 v[18:33], v[174:177], v[146:149], v[18:33]
	s_waitcnt lgkmcnt(5)
	v_mfma_f32_32x32x16_bf16 v[18:33], v[178:181], v[142:145], v[18:33]
	s_waitcnt lgkmcnt(4)
	v_mfma_f32_32x32x16_bf16 v[18:33], v[182:185], v[138:141], v[18:33]
	s_waitcnt lgkmcnt(3)
	v_mfma_f32_32x32x16_bf16 v[2:17], v[190:193], v[150:153], v[2:17]
	s_waitcnt lgkmcnt(2)
	v_mfma_f32_32x32x16_bf16 v[2:17], v[194:197], v[146:149], v[2:17]
	s_waitcnt lgkmcnt(1)
	v_mfma_f32_32x32x16_bf16 v[2:17], v[234:237], v[142:145], v[2:17]
	s_waitcnt lgkmcnt(0)
	v_mfma_f32_32x32x16_bf16 v[2:17], v[238:241], v[138:141], v[2:17]
	s_lshl_b64 s[0:1], s[0:1], 15
	v_lshl_add_u64 v[138:139], v[206:207], 0, s[0:1]
	global_load_dwordx4 v[150:153], v[138:139], off
	global_load_dwordx4 v[146:149], v[138:139], off offset:32
	global_load_dwordx4 v[142:145], v[138:139], off offset:64
	s_nop 0
	global_load_dwordx4 v[138:141], v[138:139], off offset:96
	s_branch .LBB0_200
.LBB0_209:
	s_setprio 0
	s_waitcnt vmcnt(0)
	v_cmp_eq_u32_e32 vcc, 0, v217
	s_waitcnt lgkmcnt(0)
	s_barrier
	s_and_saveexec_b64 s[0:1], vcc
	s_cbranch_execz .LBB0_212
	s_mov_b64 s[2:3], exec
	v_mbcnt_lo_u32_b32 v0, s2, 0
	buffer_wbl2 sc1
	s_waitcnt vmcnt(0)
	s_waitcnt vmcnt(0)
	v_mbcnt_hi_u32_b32 v0, s3, v0
	v_cmp_eq_u32_e32 vcc, 0, v0
	s_and_b64 s[4:5], exec, vcc
	s_mov_b64 exec, s[4:5]
	s_cbranch_execz .LBB0_212
	s_lshl_b32 s4, s11, 6
	s_ashr_i32 s5, s4, 31
	s_lshl_b64 s[4:5], s[4:5], 2
	v_readlane_b32 s6, v254, 34
	s_add_u32 s4, s6, s4
	v_readlane_b32 s6, v254, 35
	s_addc_u32 s5, s6, s5
	s_bcnt1_i32_b64 s2, s[2:3]
	v_mov_b32_e32 v0, s2
	global_atomic_add v1, v0, s[4:5]
